# gla_s1 chunk loop rewritten: two static register staging sets, k~T/v/g loads issued two chunks ahead with counted vmcnt; final grid barrier skipped after the last GEMM
# speedup vs baseline: 1.0083x; 1.0083x over previous
.LBB0_607:
	s_ashr_i32 s20, s19, 4
	s_bfe_u32 s21, s19, 0x20002
	s_lshl_b32 s12, s20, 5
	s_or_b32 s8, s12, s21
	s_ashr_i32 s9, s8, 31
	s_lshl_b64 s[10:11], s[8:9], 15
	v_lshl_add_u64 v[0:1], v[114:115], 0, s[10:11]
	v_add_co_u32_e32 v2, vcc, 0x2000, v0
	v_mov_b32_e32 v129, 0
	v_mov_b32_e32 v230, 0
	v_mov_b32_e32 v231, 0
	s_nop 0
	v_addc_co_u32_e32 v3, vcc, 0, v1, vcc
	global_load_dwordx4 v[64:67], v[0:1], off
	global_load_dwordx4 v[68:71], v[2:3], off
	v_add_co_u32_e32 v2, vcc, 0x4000, v0
	s_nop 1
	v_addc_co_u32_e32 v3, vcc, 0, v1, vcc
	v_add_co_u32_e32 v0, vcc, 0x6000, v0
	s_nop 1
	v_addc_co_u32_e32 v1, vcc, 0, v1, vcc
	global_load_dwordx4 v[72:75], v[2:3], off
	global_load_dwordx4 v[76:79], v[0:1], off
	v_mov_b32_e32 v0, 0
	s_and_saveexec_b64 s[10:11], s[0:1]
	s_cbranch_execz .LBB0_609
	s_lshl_b64 s[22:23], s[8:9], 10
	v_lshl_add_u64 v[2:3], v[116:117], 0, s[22:23]
	global_load_dword v230, v[2:3], off
.LBB0_609:
	s_or_b64 exec, exec, s[10:11]
	s_and_b32 s22, s19, 3
	s_lshr_b32 s10, s19, 2
	s_lshl_b32 s11, s22, 7
	s_and_b32 s10, s10, 3
	s_or_b32 s23, s11, s14
	s_lshl_b64 s[8:9], s[8:9], 16
	s_add_u32 s8, s4, s8
	s_addc_u32 s9, s5, s9
	v_lshl_or_b32 v160, s23, 7, v123
	v_lshl_add_u64 v[2:3], s[8:9], 0, v[160:161]
	global_load_dwordx4 v[80:83], v[2:3], off offset:3072
	global_load_dwordx4 v[84:87], v[2:3], off offset:2048
	global_load_dwordx4 v[88:91], v[2:3], off offset:1024
	global_load_dwordx4 v[92:95], v[2:3], off
	s_add_i32 s8, s12, s10
	s_mov_b32 s24, 0
	v_mov_b32_e32 v125, 1.0
	v_mov_b32_e32 v1, v0
	v_mov_b32_e32 v2, v0
	v_mov_b32_e32 v3, v0
	v_mov_b32_e32 v4, v0
	v_mov_b32_e32 v5, v0
	v_mov_b32_e32 v6, v0
	v_mov_b32_e32 v7, v0
	v_mov_b32_e32 v8, v0
	v_mov_b32_e32 v9, v0
	v_mov_b32_e32 v10, v0
	v_mov_b32_e32 v11, v0
	v_mov_b32_e32 v12, v0
	v_mov_b32_e32 v13, v0
	v_mov_b32_e32 v14, v0
	v_mov_b32_e32 v15, v0
	v_mov_b32_e32 v16, v0
	v_mov_b32_e32 v17, v0
	v_mov_b32_e32 v18, v0
	v_mov_b32_e32 v19, v0
	v_mov_b32_e32 v20, v0
	v_mov_b32_e32 v21, v0
	v_mov_b32_e32 v22, v0
	v_mov_b32_e32 v23, v0
	v_mov_b32_e32 v24, v0
	v_mov_b32_e32 v25, v0
	v_mov_b32_e32 v26, v0
	v_mov_b32_e32 v27, v0
	v_mov_b32_e32 v28, v0
	v_mov_b32_e32 v29, v0
	v_mov_b32_e32 v30, v0
	v_mov_b32_e32 v31, v0
	v_mov_b32_e32 v32, v0
	v_mov_b32_e32 v33, v0
	v_mov_b32_e32 v34, v0
	v_mov_b32_e32 v35, v0
	v_mov_b32_e32 v36, v0
	v_mov_b32_e32 v37, v0
	v_mov_b32_e32 v38, v0
	v_mov_b32_e32 v39, v0
	v_mov_b32_e32 v40, v0
	v_mov_b32_e32 v41, v0
	v_mov_b32_e32 v42, v0
	v_mov_b32_e32 v43, v0
	v_mov_b32_e32 v44, v0
	v_mov_b32_e32 v45, v0
	v_mov_b32_e32 v46, v0
	v_mov_b32_e32 v47, v0
	v_mov_b32_e32 v48, v0
	v_mov_b32_e32 v49, v0
	v_mov_b32_e32 v50, v0
	v_mov_b32_e32 v51, v0
	v_mov_b32_e32 v52, v0
	v_mov_b32_e32 v53, v0
	v_mov_b32_e32 v54, v0
	v_mov_b32_e32 v55, v0
	v_mov_b32_e32 v56, v0
	v_mov_b32_e32 v57, v0
	v_mov_b32_e32 v58, v0
	v_mov_b32_e32 v59, v0
	v_mov_b32_e32 v60, v0
	v_mov_b32_e32 v61, v0
	v_mov_b32_e32 v62, v0
	v_mov_b32_e32 v63, v0
	v_lshl_add_u64 v[152:153], s[4:5], 0, v[160:161]
	s_add_i32 s8, s8, 4
	s_ashr_i32 s9, s8, 31
	s_lshl_b64 s[10:11], s[8:9], 15
	v_lshl_add_u64 v[154:155], v[114:115], 0, s[10:11]
	global_load_dwordx4 v[198:201], v[154:155], off
	v_add_co_u32_e32 v156, vcc, 0x2000, v154
	s_nop 1
	v_addc_co_u32_e32 v157, vcc, 0, v155, vcc
	global_load_dwordx4 v[202:205], v[156:157], off
	v_add_co_u32_e32 v156, vcc, 0x4000, v154
	s_nop 1
	v_addc_co_u32_e32 v157, vcc, 0, v155, vcc
	global_load_dwordx4 v[206:209], v[156:157], off
	v_add_co_u32_e32 v156, vcc, 0x6000, v154
	s_nop 1
	v_addc_co_u32_e32 v157, vcc, 0, v155, vcc
	global_load_dwordx4 v[210:213], v[156:157], off
	s_lshl_b64 s[10:11], s[8:9], 16
	v_lshl_add_u64 v[154:155], v[152:153], 0, s[10:11]
	global_load_dwordx4 v[226:229], v[154:155], off
	global_load_dwordx4 v[222:225], v[154:155], off offset:1024
	global_load_dwordx4 v[218:221], v[154:155], off offset:2048
	global_load_dwordx4 v[214:217], v[154:155], off offset:3072
	s_and_saveexec_b64 s[10:11], s[0:1]
	s_cbranch_execz .Lmy_s1_p1
	s_lshl_b64 s[12:13], s[8:9], 10
	v_lshl_add_u64 v[154:155], v[116:117], 0, s[12:13]
	global_load_dword v231, v[154:155], off
.Lmy_s1_p1:
	s_or_b64 exec, exec, s[10:11]
	s_waitcnt lgkmcnt(0)
	s_branch .Lmy_s1_top
.LBB0_610:
.Lmy_s1_top:
	s_cmp_lt_u32 s24, 6
	s_cselect_b64 s[10:11], -1, 0
	s_and_b32 s9, s24, 1
	s_lshl_b32 s25, s9, 15
	s_lshl_b32 s26, s9, 10
	s_bitset1_b32 s26, 16
	v_lshl_add_u32 v127, v112, 4, s25
	s_cmp_eq_u32 s9, 0
	s_cbranch_scc0 .Lmy_s1_odd
	s_waitcnt vmcnt(8)
	v_mov_b64_e32 v[96:97], v[80:81]
	v_mov_b64_e32 v[98:99], v[82:83]
	v_mov_b64_e32 v[100:101], v[84:85]
	v_mov_b64_e32 v[102:103], v[86:87]
	v_mov_b64_e32 v[104:105], v[88:89]
	v_mov_b64_e32 v[106:107], v[90:91]
	v_mov_b64_e32 v[108:109], v[92:93]
	v_mov_b64_e32 v[110:111], v[94:95]
	v_mov_b32_e32 v129, v230
	ds_write_b128 v127, v[64:67]
	ds_write_b128 v127, v[68:71] offset:8192
	ds_write_b128 v127, v[72:75] offset:16384
	ds_write_b128 v127, v[76:79] offset:24576
	s_and_saveexec_b64 s[12:13], s[0:1]
	v_lshl_add_u32 v127, v112, 2, s26
	ds_write_b32 v127, v129
	s_or_b64 exec, exec, s[12:13]
	s_waitcnt lgkmcnt(0)
	s_barrier
	s_andn2_b64 vcc, exec, s[10:11]
	s_cbranch_vccnz .LBB0_618
	s_add_i32 s12, s8, 4
	s_ashr_i32 s13, s12, 31
	s_lshl_b64 s[10:11], s[12:13], 15
	v_lshl_add_u64 v[154:155], v[114:115], 0, s[10:11]
	global_load_dwordx4 v[64:67], v[154:155], off
	v_add_co_u32_e32 v156, vcc, 0x2000, v154
	s_nop 1
	v_addc_co_u32_e32 v157, vcc, 0, v155, vcc
	global_load_dwordx4 v[68:71], v[156:157], off
	v_add_co_u32_e32 v156, vcc, 0x4000, v154
	s_nop 1
	v_addc_co_u32_e32 v157, vcc, 0, v155, vcc
	global_load_dwordx4 v[72:75], v[156:157], off
	v_add_co_u32_e32 v156, vcc, 0x6000, v154
	s_nop 1
	v_addc_co_u32_e32 v157, vcc, 0, v155, vcc
	global_load_dwordx4 v[76:79], v[156:157], off
	s_lshl_b64 s[10:11], s[12:13], 16
	v_lshl_add_u64 v[154:155], v[152:153], 0, s[10:11]
	global_load_dwordx4 v[92:95], v[154:155], off
	global_load_dwordx4 v[88:91], v[154:155], off offset:1024
	global_load_dwordx4 v[84:87], v[154:155], off offset:2048
	global_load_dwordx4 v[80:83], v[154:155], off offset:3072
	s_and_saveexec_b64 s[10:11], s[0:1]
	s_cbranch_execz .Lmy_s1_e_pg
	s_lshl_b64 s[12:13], s[12:13], 10
	v_lshl_add_u64 v[154:155], v[116:117], 0, s[12:13]
	global_load_dword v230, v[154:155], off
.Lmy_s1_e_pg:
	s_or_b64 exec, exec, s[10:11]
	s_branch .LBB0_618
.Lmy_s1_odd:
	s_cmp_eq_u32 s24, 7
	s_cbranch_scc1 .Lmy_s1_o_w0
	s_waitcnt vmcnt(8)
	s_branch .Lmy_s1_o_go

.Lmy_s1_o_go:
	v_mov_b64_e32 v[96:97], v[214:215]
	v_mov_b64_e32 v[98:99], v[216:217]
	v_mov_b64_e32 v[100:101], v[218:219]
	v_mov_b64_e32 v[102:103], v[220:221]
	v_mov_b64_e32 v[104:105], v[222:223]
	v_mov_b64_e32 v[106:107], v[224:225]
	v_mov_b64_e32 v[108:109], v[226:227]
	v_mov_b64_e32 v[110:111], v[228:229]
	v_mov_b32_e32 v129, v231
	ds_write_b128 v127, v[198:201]
	ds_write_b128 v127, v[202:205] offset:8192
	ds_write_b128 v127, v[206:209] offset:16384
	ds_write_b128 v127, v[210:213] offset:24576
	s_and_saveexec_b64 s[12:13], s[0:1]
	v_lshl_add_u32 v127, v112, 2, s26
	ds_write_b32 v127, v129
	s_or_b64 exec, exec, s[12:13]
	s_waitcnt lgkmcnt(0)
	s_barrier
	s_andn2_b64 vcc, exec, s[10:11]
	s_cbranch_vccnz .LBB0_618
	s_add_i32 s12, s8, 4
	s_ashr_i32 s13, s12, 31
	s_lshl_b64 s[10:11], s[12:13], 15
	v_lshl_add_u64 v[154:155], v[114:115], 0, s[10:11]
	global_load_dwordx4 v[198:201], v[154:155], off
	v_add_co_u32_e32 v156, vcc, 0x2000, v154
	s_nop 1
	v_addc_co_u32_e32 v157, vcc, 0, v155, vcc
	global_load_dwordx4 v[202:205], v[156:157], off
	v_add_co_u32_e32 v156, vcc, 0x4000, v154
	s_nop 1
	v_addc_co_u32_e32 v157, vcc, 0, v155, vcc
	global_load_dwordx4 v[206:209], v[156:157], off
	v_add_co_u32_e32 v156, vcc, 0x6000, v154
	s_nop 1
	v_addc_co_u32_e32 v157, vcc, 0, v155, vcc
	global_load_dwordx4 v[210:213], v[156:157], off
	s_lshl_b64 s[10:11], s[12:13], 16
	v_lshl_add_u64 v[154:155], v[152:153], 0, s[10:11]
	global_load_dwordx4 v[226:229], v[154:155], off
	global_load_dwordx4 v[222:225], v[154:155], off offset:1024
	global_load_dwordx4 v[218:221], v[154:155], off offset:2048
	global_load_dwordx4 v[214:217], v[154:155], off offset:3072
	s_and_saveexec_b64 s[10:11], s[0:1]
	s_cbranch_execz .Lmy_s1_o_pg
	s_lshl_b64 s[12:13], s[12:13], 10
	v_lshl_add_u64 v[154:155], v[116:117], 0, s[12:13]
	global_load_dword v231, v[154:155], off

.LBB0_618:
	v_cndmask_b32_e64 v129, 1.0, v129, s[0:1]
	s_add_i32 s26, s26, s15
	v_mul_f32_e32 v125, v125, v129
	v_add_u32_e32 v129, s26, v113
	ds_read_b128 v[154:157], v129
	ds_read_b128 v[170:173], v129 offset:32
	ds_read_b128 v[174:177], v129 offset:64
	ds_read_b128 v[178:181], v129 offset:96
	s_add_i32 s9, s16, s25
	s_waitcnt lgkmcnt(0)
	v_pk_mul_f32 v[48:49], v[48:49], v[154:155]
	v_pk_mul_f32 v[52:53], v[52:53], v[170:171]
	v_pk_mul_f32 v[56:57], v[56:57], v[174:175]
	v_pk_mul_f32 v[60:61], v[60:61], v[178:179]
	v_pk_mul_f32 v[62:63], v[62:63], v[180:181]
	v_pk_mul_f32 v[58:59], v[58:59], v[176:177]
	v_pk_mul_f32 v[54:55], v[54:55], v[172:173]
	v_pk_mul_f32 v[50:51], v[50:51], v[156:157]
	ds_read_b128 v[154:157], v129 offset:128
	ds_read_b128 v[170:173], v129 offset:160
	ds_read_b128 v[174:177], v129 offset:192
	ds_read_b128 v[178:181], v129 offset:224
	s_add_i32 s24, s24, 1
	s_waitcnt lgkmcnt(0)
	v_pk_mul_f32 v[32:33], v[32:33], v[154:155]
	v_pk_mul_f32 v[36:37], v[36:37], v[170:171]
	v_pk_mul_f32 v[40:41], v[40:41], v[174:175]
	v_pk_mul_f32 v[44:45], v[44:45], v[178:179]
	v_pk_mul_f32 v[46:47], v[46:47], v[180:181]
	v_pk_mul_f32 v[42:43], v[42:43], v[176:177]
	v_pk_mul_f32 v[38:39], v[38:39], v[172:173]
	v_pk_mul_f32 v[34:35], v[34:35], v[156:157]
	ds_read_b128 v[154:157], v129 offset:256
	ds_read_b128 v[170:173], v129 offset:288
	ds_read_b128 v[174:177], v129 offset:320
	ds_read_b128 v[178:181], v129 offset:352
	s_add_i32 s8, s8, 4
	s_waitcnt lgkmcnt(0)
	v_pk_mul_f32 v[16:17], v[16:17], v[154:155]
	v_pk_mul_f32 v[20:21], v[20:21], v[170:171]
	v_pk_mul_f32 v[24:25], v[24:25], v[174:175]
	v_pk_mul_f32 v[28:29], v[28:29], v[178:179]
	v_pk_mul_f32 v[30:31], v[30:31], v[180:181]
	v_pk_mul_f32 v[26:27], v[26:27], v[176:177]
	v_pk_mul_f32 v[22:23], v[22:23], v[172:173]
	v_pk_mul_f32 v[18:19], v[18:19], v[156:157]
	ds_read_b128 v[154:157], v129 offset:384
	ds_read_b128 v[170:173], v129 offset:416
	ds_read_b128 v[174:177], v129 offset:448
	ds_read_b128 v[178:181], v129 offset:480
	v_add_u32_e32 v129, s9, v119
	s_waitcnt lgkmcnt(0)
	v_pk_mul_f32 v[0:1], v[0:1], v[154:155]
	v_pk_mul_f32 v[2:3], v[2:3], v[156:157]
	ds_read_b128 v[154:157], v129
	s_waitcnt lgkmcnt(0)
	v_mfma_f32_32x32x16_bf16 v[48:63], v[154:157], v[108:111], v[48:63]
	ds_read_b128 v[154:157], v129 offset:4096
	v_mul_f32_e64 v12, v12, v178
	v_mul_f32_e64 v13, v13, v179
	v_mul_f32_e64 v8, v8, v174
	v_mul_f32_e64 v9, v9, v175
	v_pk_mul_f32 v[4:5], v[4:5], v[170:171]
	v_pk_mul_f32 v[14:15], v[14:15], v[180:181]
	v_pk_mul_f32 v[10:11], v[10:11], v[176:177]
	v_pk_mul_f32 v[6:7], v[6:7], v[172:173]
	s_waitcnt lgkmcnt(0)
	v_mfma_f32_32x32x16_bf16 v[32:47], v[154:157], v[108:111], v[32:47]
	ds_read_b128 v[154:157], v129 offset:8192
	s_cmp_eq_u32 s24, 8
	s_waitcnt lgkmcnt(0)
	v_mfma_f32_32x32x16_bf16 v[16:31], v[154:157], v[108:111], v[16:31]
	ds_read_b128 v[154:157], v129 offset:12288
	s_waitcnt lgkmcnt(0)
	v_mfma_f32_32x32x16_bf16 v[0:15], v[154:157], v[108:111], v[0:15]
	ds_read_b128 v[108:111], v129 offset:1024
	s_waitcnt lgkmcnt(0)
	v_mfma_f32_32x32x16_bf16 v[48:63], v[108:111], v[104:107], v[48:63]
	ds_read_b128 v[108:111], v129 offset:5120
	s_waitcnt lgkmcnt(0)
	v_mfma_f32_32x32x16_bf16 v[32:47], v[108:111], v[104:107], v[32:47]
	ds_read_b128 v[108:111], v129 offset:9216
	s_waitcnt lgkmcnt(0)
	v_mfma_f32_32x32x16_bf16 v[16:31], v[108:111], v[104:107], v[16:31]
	ds_read_b128 v[108:111], v129 offset:13312
	s_waitcnt lgkmcnt(0)
	v_mfma_f32_32x32x16_bf16 v[0:15], v[108:111], v[104:107], v[0:15]
	ds_read_b128 v[104:107], v129 offset:2048
	s_waitcnt lgkmcnt(0)
	v_mfma_f32_32x32x16_bf16 v[48:63], v[104:107], v[100:103], v[48:63]
	ds_read_b128 v[104:107], v129 offset:6144
	s_waitcnt lgkmcnt(0)
	v_mfma_f32_32x32x16_bf16 v[32:47], v[104:107], v[100:103], v[32:47]
	ds_read_b128 v[104:107], v129 offset:10240
	s_waitcnt lgkmcnt(0)
	v_mfma_f32_32x32x16_bf16 v[16:31], v[104:107], v[100:103], v[16:31]
	ds_read_b128 v[104:107], v129 offset:14336
	s_waitcnt lgkmcnt(0)
	v_mfma_f32_32x32x16_bf16 v[0:15], v[104:107], v[100:103], v[0:15]
	ds_read_b128 v[100:103], v129 offset:3072
	s_waitcnt lgkmcnt(0)
	v_mfma_f32_32x32x16_bf16 v[48:63], v[100:103], v[96:99], v[48:63]
	ds_read_b128 v[100:103], v129 offset:7168
	s_waitcnt lgkmcnt(0)
	v_mfma_f32_32x32x16_bf16 v[32:47], v[100:103], v[96:99], v[32:47]
	ds_read_b128 v[100:103], v129 offset:11264
	s_waitcnt lgkmcnt(0)
	v_mfma_f32_32x32x16_bf16 v[16:31], v[100:103], v[96:99], v[16:31]
	ds_read_b128 v[100:103], v129 offset:15360
	s_waitcnt lgkmcnt(0)
	v_mfma_f32_32x32x16_bf16 v[0:15], v[100:103], v[96:99], v[0:15]
	s_cbranch_scc0 .LBB0_610
	s_lshl_b32 s8, s20, 2
	s_or_b32 s8, s8, s21
	s_ashr_i32 s9, s8, 31
	s_lshl_b64 s[10:11], s[8:9], 8
	s_add_u32 s9, s10, s17
	s_addc_u32 s8, s11, s18
	s_lshl_b32 s38, s23, 2
	s_waitcnt vmcnt(0)
	v_mov_b32_e32 v67, s8
	v_or_b32_e32 v66, s9, v118
	v_lshl_add_u64 v[64:65], v[120:121], 0, s[38:39]
	v_lshlrev_b64 v[66:67], 11, v[66:67]
	v_lshl_add_u64 v[66:67], v[64:65], 0, v[66:67]
	global_store_dword v[66:67], v48, off
	v_mov_b32_e32 v67, s8
	v_or_b32_e32 v66, s9, v122
	v_lshlrev_b64 v[66:67], 11, v[66:67]
	v_lshl_add_u64 v[66:67], v[64:65], 0, v[66:67]
	global_store_dword v[66:67], v49, off
	v_mov_b32_e32 v49, s8
	v_or_b32_e32 v48, s9, v124
	v_lshlrev_b64 v[48:49], 11, v[48:49]
	v_lshl_add_u64 v[48:49], v[64:65], 0, v[48:49]
	global_store_dword v[48:49], v50, off
	v_mov_b32_e32 v49, s8
	v_or_b32_e32 v48, s9, v126
	v_lshlrev_b64 v[48:49], 11, v[48:49]
	v_lshl_add_u64 v[48:49], v[64:65], 0, v[48:49]
	global_store_dword v[48:49], v51, off
	v_mov_b32_e32 v49, s8
	v_or_b32_e32 v48, s9, v128
	v_lshlrev_b64 v[48:49], 11, v[48:49]
	v_lshl_add_u64 v[48:49], v[64:65], 0, v[48:49]
	global_store_dword v[48:49], v52, off
	v_mov_b32_e32 v49, s8
	v_or_b32_e32 v48, s9, v130
	v_lshlrev_b64 v[48:49], 11, v[48:49]
	v_lshl_add_u64 v[48:49], v[64:65], 0, v[48:49]
	global_store_dword v[48:49], v53, off
	v_mov_b32_e32 v49, s8
	v_or_b32_e32 v48, s9, v132
	v_lshlrev_b64 v[48:49], 11, v[48:49]
	v_lshl_add_u64 v[48:49], v[64:65], 0, v[48:49]
	global_store_dword v[48:49], v54, off
	v_mov_b32_e32 v49, s8
	v_or_b32_e32 v48, s9, v134
	v_lshlrev_b64 v[48:49], 11, v[48:49]
	v_lshl_add_u64 v[48:49], v[64:65], 0, v[48:49]
	global_store_dword v[48:49], v55, off
	v_mov_b32_e32 v49, s8
	v_or_b32_e32 v48, s9, v136
	v_lshlrev_b64 v[48:49], 11, v[48:49]
	v_lshl_add_u64 v[48:49], v[64:65], 0, v[48:49]
	global_store_dword v[48:49], v56, off
	v_mov_b32_e32 v49, s8
	v_or_b32_e32 v48, s9, v138
	v_lshlrev_b64 v[48:49], 11, v[48:49]
	v_lshl_add_u64 v[48:49], v[64:65], 0, v[48:49]
	global_store_dword v[48:49], v57, off
	v_mov_b32_e32 v49, s8
	v_or_b32_e32 v48, s9, v140
	v_lshlrev_b64 v[48:49], 11, v[48:49]
	v_lshl_add_u64 v[48:49], v[64:65], 0, v[48:49]
	global_store_dword v[48:49], v58, off
	v_mov_b32_e32 v49, s8
	v_or_b32_e32 v48, s9, v142
	v_lshlrev_b64 v[48:49], 11, v[48:49]
	v_lshl_add_u64 v[48:49], v[64:65], 0, v[48:49]
	global_store_dword v[48:49], v59, off
	v_mov_b32_e32 v49, s8
	v_or_b32_e32 v48, s9, v144
	v_lshlrev_b64 v[48:49], 11, v[48:49]
	v_lshl_add_u64 v[48:49], v[64:65], 0, v[48:49]
	global_store_dword v[48:49], v60, off
	v_mov_b32_e32 v49, s8
	v_or_b32_e32 v48, s9, v146
	v_lshlrev_b64 v[48:49], 11, v[48:49]
	v_lshl_add_u64 v[48:49], v[64:65], 0, v[48:49]
	global_store_dword v[48:49], v61, off
	v_mov_b32_e32 v49, s8
	v_or_b32_e32 v48, s9, v148
	v_lshlrev_b64 v[48:49], 11, v[48:49]
	v_lshl_add_u64 v[48:49], v[64:65], 0, v[48:49]
	global_store_dword v[48:49], v62, off
	v_mov_b32_e32 v49, s8
	v_or_b32_e32 v48, s9, v150
	v_lshlrev_b64 v[48:49], 11, v[48:49]
	v_lshl_add_u64 v[48:49], v[64:65], 0, v[48:49]
	s_or_b32 s10, s9, 32
	global_store_dword v[48:49], v63, off
	v_mov_b32_e32 v49, s8
	v_or_b32_e32 v48, s10, v118
	v_lshlrev_b64 v[48:49], 11, v[48:49]
	v_lshl_add_u64 v[48:49], v[64:65], 0, v[48:49]
	global_store_dword v[48:49], v32, off
	v_mov_b32_e32 v49, s8
	v_or_b32_e32 v48, s10, v122
	v_lshlrev_b64 v[48:49], 11, v[48:49]
	v_lshl_add_u64 v[48:49], v[64:65], 0, v[48:49]
	global_store_dword v[48:49], v33, off
	v_mov_b32_e32 v33, s8
	v_or_b32_e32 v32, s10, v124
	v_lshlrev_b64 v[32:33], 11, v[32:33]
	v_lshl_add_u64 v[32:33], v[64:65], 0, v[32:33]
	global_store_dword v[32:33], v34, off
	v_mov_b32_e32 v33, s8
	v_or_b32_e32 v32, s10, v126
	v_lshlrev_b64 v[32:33], 11, v[32:33]
	v_lshl_add_u64 v[32:33], v[64:65], 0, v[32:33]
	global_store_dword v[32:33], v35, off
	v_mov_b32_e32 v33, s8
	v_or_b32_e32 v32, s10, v128
	v_lshlrev_b64 v[32:33], 11, v[32:33]
	v_lshl_add_u64 v[32:33], v[64:65], 0, v[32:33]
	global_store_dword v[32:33], v36, off
	v_mov_b32_e32 v33, s8
	v_or_b32_e32 v32, s10, v130
	v_lshlrev_b64 v[32:33], 11, v[32:33]
	v_lshl_add_u64 v[32:33], v[64:65], 0, v[32:33]
	global_store_dword v[32:33], v37, off
	v_mov_b32_e32 v33, s8
	v_or_b32_e32 v32, s10, v132
	v_lshlrev_b64 v[32:33], 11, v[32:33]
	v_lshl_add_u64 v[32:33], v[64:65], 0, v[32:33]
	global_store_dword v[32:33], v38, off
	v_mov_b32_e32 v33, s8
	v_or_b32_e32 v32, s10, v134
	v_lshlrev_b64 v[32:33], 11, v[32:33]
	v_lshl_add_u64 v[32:33], v[64:65], 0, v[32:33]
	global_store_dword v[32:33], v39, off
	v_mov_b32_e32 v33, s8
	v_or_b32_e32 v32, s10, v136
	v_lshlrev_b64 v[32:33], 11, v[32:33]
	v_lshl_add_u64 v[32:33], v[64:65], 0, v[32:33]
	global_store_dword v[32:33], v40, off
	v_mov_b32_e32 v33, s8
	v_or_b32_e32 v32, s10, v138
	v_lshlrev_b64 v[32:33], 11, v[32:33]
	v_lshl_add_u64 v[32:33], v[64:65], 0, v[32:33]
	global_store_dword v[32:33], v41, off
	v_mov_b32_e32 v33, s8
	v_or_b32_e32 v32, s10, v140
	v_lshlrev_b64 v[32:33], 11, v[32:33]
	v_lshl_add_u64 v[32:33], v[64:65], 0, v[32:33]
	global_store_dword v[32:33], v42, off
	v_mov_b32_e32 v33, s8
	v_or_b32_e32 v32, s10, v142
	v_lshlrev_b64 v[32:33], 11, v[32:33]
	v_lshl_add_u64 v[32:33], v[64:65], 0, v[32:33]
	global_store_dword v[32:33], v43, off
	v_mov_b32_e32 v33, s8
	v_or_b32_e32 v32, s10, v144
	v_lshlrev_b64 v[32:33], 11, v[32:33]
	v_lshl_add_u64 v[32:33], v[64:65], 0, v[32:33]
	global_store_dword v[32:33], v44, off
	v_mov_b32_e32 v33, s8
	v_or_b32_e32 v32, s10, v146
	v_lshlrev_b64 v[32:33], 11, v[32:33]
	v_lshl_add_u64 v[32:33], v[64:65], 0, v[32:33]
	global_store_dword v[32:33], v45, off
	v_mov_b32_e32 v33, s8
	v_or_b32_e32 v32, s10, v148
	v_lshlrev_b64 v[32:33], 11, v[32:33]
	v_lshl_add_u64 v[32:33], v[64:65], 0, v[32:33]
	global_store_dword v[32:33], v46, off
	v_mov_b32_e32 v33, s8
	v_or_b32_e32 v32, s10, v150
	v_lshlrev_b64 v[32:33], 11, v[32:33]
	v_lshl_add_u64 v[32:33], v[64:65], 0, v[32:33]
	s_or_b32 s10, s9, 64
	global_store_dword v[32:33], v47, off
	v_mov_b32_e32 v33, s8
	v_or_b32_e32 v32, s10, v118
	v_lshlrev_b64 v[32:33], 11, v[32:33]
	v_lshl_add_u64 v[32:33], v[64:65], 0, v[32:33]
	global_store_dword v[32:33], v16, off
	v_mov_b32_e32 v33, s8
	v_or_b32_e32 v32, s10, v122
	v_lshlrev_b64 v[32:33], 11, v[32:33]
	v_lshl_add_u64 v[32:33], v[64:65], 0, v[32:33]
	global_store_dword v[32:33], v17, off
	v_mov_b32_e32 v17, s8
	v_or_b32_e32 v16, s10, v124
	v_lshlrev_b64 v[16:17], 11, v[16:17]
	v_lshl_add_u64 v[16:17], v[64:65], 0, v[16:17]
	global_store_dword v[16:17], v18, off
	v_mov_b32_e32 v17, s8
	v_or_b32_e32 v16, s10, v126
	v_lshlrev_b64 v[16:17], 11, v[16:17]
	v_lshl_add_u64 v[16:17], v[64:65], 0, v[16:17]
	global_store_dword v[16:17], v19, off
	v_mov_b32_e32 v17, s8
	v_or_b32_e32 v16, s10, v128
	v_lshlrev_b64 v[16:17], 11, v[16:17]
	v_lshl_add_u64 v[16:17], v[64:65], 0, v[16:17]
	global_store_dword v[16:17], v20, off
	v_mov_b32_e32 v17, s8
	v_or_b32_e32 v16, s10, v130
	v_lshlrev_b64 v[16:17], 11, v[16:17]
	v_lshl_add_u64 v[16:17], v[64:65], 0, v[16:17]
	global_store_dword v[16:17], v21, off
	v_mov_b32_e32 v17, s8
	v_or_b32_e32 v16, s10, v132
	v_lshlrev_b64 v[16:17], 11, v[16:17]
	v_lshl_add_u64 v[16:17], v[64:65], 0, v[16:17]
	global_store_dword v[16:17], v22, off
	v_mov_b32_e32 v17, s8
	v_or_b32_e32 v16, s10, v134
	v_lshlrev_b64 v[16:17], 11, v[16:17]
	v_lshl_add_u64 v[16:17], v[64:65], 0, v[16:17]
	global_store_dword v[16:17], v23, off
	v_mov_b32_e32 v17, s8
	v_or_b32_e32 v16, s10, v136
	v_lshlrev_b64 v[16:17], 11, v[16:17]
	v_lshl_add_u64 v[16:17], v[64:65], 0, v[16:17]
	global_store_dword v[16:17], v24, off
	v_mov_b32_e32 v17, s8
	v_or_b32_e32 v16, s10, v138
	v_lshlrev_b64 v[16:17], 11, v[16:17]
	v_lshl_add_u64 v[16:17], v[64:65], 0, v[16:17]
	global_store_dword v[16:17], v25, off
	v_mov_b32_e32 v17, s8
	v_or_b32_e32 v16, s10, v140
	v_lshlrev_b64 v[16:17], 11, v[16:17]
	v_lshl_add_u64 v[16:17], v[64:65], 0, v[16:17]
	global_store_dword v[16:17], v26, off
	v_mov_b32_e32 v17, s8
	v_or_b32_e32 v16, s10, v142
	v_lshlrev_b64 v[16:17], 11, v[16:17]
	v_lshl_add_u64 v[16:17], v[64:65], 0, v[16:17]
	global_store_dword v[16:17], v27, off
	v_mov_b32_e32 v17, s8
	v_or_b32_e32 v16, s10, v144
	v_lshlrev_b64 v[16:17], 11, v[16:17]
	v_lshl_add_u64 v[16:17], v[64:65], 0, v[16:17]
	global_store_dword v[16:17], v28, off
	v_mov_b32_e32 v17, s8
	v_or_b32_e32 v16, s10, v146
	v_lshlrev_b64 v[16:17], 11, v[16:17]
	v_lshl_add_u64 v[16:17], v[64:65], 0, v[16:17]
	global_store_dword v[16:17], v29, off
	v_mov_b32_e32 v17, s8
	v_or_b32_e32 v16, s10, v148
	v_lshlrev_b64 v[16:17], 11, v[16:17]
	v_lshl_add_u64 v[16:17], v[64:65], 0, v[16:17]
	global_store_dword v[16:17], v30, off
	v_mov_b32_e32 v17, s8
	v_or_b32_e32 v16, s10, v150
	v_lshlrev_b64 v[16:17], 11, v[16:17]
	v_lshl_add_u64 v[16:17], v[64:65], 0, v[16:17]
	s_or_b32 s9, s9, 0x60
	global_store_dword v[16:17], v31, off
	v_mov_b32_e32 v17, s8
	v_or_b32_e32 v16, s9, v118
	v_lshlrev_b64 v[16:17], 11, v[16:17]
	v_lshl_add_u64 v[16:17], v[64:65], 0, v[16:17]
	global_store_dword v[16:17], v0, off
	v_mov_b32_e32 v17, s8
	v_or_b32_e32 v16, s9, v122
	v_lshlrev_b64 v[16:17], 11, v[16:17]
	v_lshl_add_u64 v[16:17], v[64:65], 0, v[16:17]
	global_store_dword v[16:17], v1, off
	v_mov_b32_e32 v1, s8
	v_or_b32_e32 v0, s9, v124
	v_lshlrev_b64 v[0:1], 11, v[0:1]
	v_lshl_add_u64 v[0:1], v[64:65], 0, v[0:1]
	global_store_dword v[0:1], v2, off
	v_mov_b32_e32 v1, s8
	v_or_b32_e32 v0, s9, v126
	v_lshlrev_b64 v[0:1], 11, v[0:1]
	v_lshl_add_u64 v[0:1], v[64:65], 0, v[0:1]
	global_store_dword v[0:1], v3, off
	v_mov_b32_e32 v1, s8
	v_or_b32_e32 v0, s9, v128
	v_lshlrev_b64 v[0:1], 11, v[0:1]
	v_lshl_add_u64 v[0:1], v[64:65], 0, v[0:1]
	global_store_dword v[0:1], v4, off
	v_mov_b32_e32 v1, s8
	v_or_b32_e32 v0, s9, v130
	v_lshlrev_b64 v[0:1], 11, v[0:1]
	v_lshl_add_u64 v[0:1], v[64:65], 0, v[0:1]
	global_store_dword v[0:1], v5, off
	v_mov_b32_e32 v1, s8
	v_or_b32_e32 v0, s9, v132
	v_lshlrev_b64 v[0:1], 11, v[0:1]
	v_lshl_add_u64 v[0:1], v[64:65], 0, v[0:1]
	global_store_dword v[0:1], v6, off
	v_mov_b32_e32 v1, s8
	v_or_b32_e32 v0, s9, v134
	v_lshlrev_b64 v[0:1], 11, v[0:1]
	v_lshl_add_u64 v[0:1], v[64:65], 0, v[0:1]
	global_store_dword v[0:1], v7, off
	v_mov_b32_e32 v1, s8
	v_or_b32_e32 v0, s9, v136
	v_lshlrev_b64 v[0:1], 11, v[0:1]
	v_lshl_add_u64 v[0:1], v[64:65], 0, v[0:1]
	global_store_dword v[0:1], v8, off
	v_mov_b32_e32 v1, s8
	v_or_b32_e32 v0, s9, v138
	v_lshlrev_b64 v[0:1], 11, v[0:1]
	v_lshl_add_u64 v[0:1], v[64:65], 0, v[0:1]
	global_store_dword v[0:1], v9, off
	v_mov_b32_e32 v1, s8
	v_or_b32_e32 v0, s9, v140
	v_lshlrev_b64 v[0:1], 11, v[0:1]
	v_lshl_add_u64 v[0:1], v[64:65], 0, v[0:1]
	global_store_dword v[0:1], v10, off
	v_mov_b32_e32 v1, s8
	v_or_b32_e32 v0, s9, v142
	v_lshlrev_b64 v[0:1], 11, v[0:1]
	v_lshl_add_u64 v[0:1], v[64:65], 0, v[0:1]
	global_store_dword v[0:1], v11, off
	v_mov_b32_e32 v1, s8
	v_or_b32_e32 v0, s9, v144
	v_lshlrev_b64 v[0:1], 11, v[0:1]
	v_lshl_add_u64 v[0:1], v[64:65], 0, v[0:1]
	global_store_dword v[0:1], v12, off
	v_mov_b32_e32 v1, s8
	v_or_b32_e32 v0, s9, v146
	v_lshlrev_b64 v[0:1], 11, v[0:1]
	v_lshl_add_u64 v[0:1], v[64:65], 0, v[0:1]
	global_store_dword v[0:1], v13, off
	v_mov_b32_e32 v1, s8
	v_or_b32_e32 v0, s9, v148
	v_lshlrev_b64 v[0:1], 11, v[0:1]
	v_lshl_add_u64 v[0:1], v[64:65], 0, v[0:1]
	global_store_dword v[0:1], v14, off
	v_mov_b32_e32 v1, s8
	v_or_b32_e32 v0, s9, v150
	s_cmp_eq_u32 s22, 0
	v_lshlrev_b64 v[0:1], 11, v[0:1]
	s_cselect_b64 s[8:9], -1, 0
	v_lshl_add_u64 v[0:1], v[64:65], 0, v[0:1]
	s_and_b64 s[10:11], s[0:1], s[8:9]
	global_store_dword v[0:1], v15, off
	s_and_saveexec_b64 s[8:9], s[10:11]
	s_cbranch_execz .LBB0_606
	s_lshl_b32 s10, s21, 8
	s_lshl_b32 s11, s20, 10
	s_or_b32 s10, s10, s11
	v_add_u32_e32 v0, s10, v112
	v_ashrrev_i32_e32 v1, 31, v0
	v_lshl_add_u64 v[0:1], v[0:1], 2, s[6:7]
	global_store_dword v[0:1], v125, off
	s_branch .LBB0_606

.LBB0_966:
	s_endpgm
	s_waitcnt vmcnt(0)
	v_readlane_b32 s30, v254, 63
	v_readlane_b32 s44, v255, 1
	v_readlane_b32 s46, v255, 3
	v_readlane_b32 s56, v255, 5
	v_readlane_b32 s54, v255, 7
	v_readlane_b32 s58, v255, 13
	v_readlane_b32 s31, v255, 0
	v_readlane_b32 s45, v255, 2
	v_readlane_b32 s47, v255, 4
	v_readlane_b32 s57, v255, 6
	v_readlane_b32 s55, v255, 8
	v_readlane_b32 s59, v255, 14
	s_barrier
